# attention: second-half softmax and next-tile LDS staging issued inside PV MFMA gaps (own-wave MFMA shadow), max3 rowmax; GDN solve packed-FMA rewrite
# speedup vs baseline: 1.0166x; 1.0166x over previous
; #define LAS __attribute__((address_space(3)))
; template <int DQK, bool QNORM, bool ONORM> DI void attn_unit(const Ctx& C, const AttnUnit& U) {
;     ...
;     auto lstore = [&](int buf) {
;         LAS unsigned char* kb = C.lds + AT_K0 + buf * AT_KSZ; LAS unsigned char* vb = C.lds + AT_V0 + buf * AT_VSZ;
; #pragma unroll
;         for (int i = 0; i < NKC; ++i) *(LAS u32x4*)(kb + krow[i] * KP + 16 * kc16[i]) = kreg[i];
;         *(LAS u32x2*)(vb + vdv0 * 136 + 16 * vk8) = (u32x2){vreg[0].x, vreg[0].y}; *(LAS u32x2*)(vb + vdv0 * 136 + 16 * vk8 + 8) = (u32x2){vreg[0].z, vreg[0].w};
;         *(LAS u32x2*)(vb + (vdv0 + 64) * 136 + 16 * vk8) = (u32x2){vreg[1].x, vreg[1].y}; *(LAS u32x2*)(vb + (vdv0 + 64) * 136 + 16 * vk8 + 8) = (u32x2){vreg[1].z, vreg[1].w};
;     };
;     ...
;             float mx = fmaxf(s0[0], s1[0]);
; #pragma unroll
;             for (int r = 1; r < 16; ++r) mx = fmaxf(mx, fmaxf(s0[r], s1[r]));
;             { auto rr = __builtin_amdgcn_permlane32_swap(__float_as_uint(mx), __float_as_uint(mx), false, false); mx = fmaxf(__uint_as_float(rr[0]), __uint_as_float(rr[1])); }
;             const float mnew = fmaxf(mrun, mx);
;             if (__any(mnew > mrun)) {
;                 const float alpha = __builtin_amdgcn_exp2f(mrun - mnew); lrun *= alpha;
; #pragma unroll
;                 for (int dt = 0; dt < 4; ++dt)
; #pragma unroll
;                     for (int r = 0; r < 16; ++r) o[dt][r] *= alpha;
;             }
.LBB0_849:
	s_nop 5
	v_max3_f32 v0, v80, v81, v82
	v_max3_f32 v219, v96, v97, v98
	v_max3_f32 v0, v0, v83, v84
	v_max3_f32 v219, v219, v99, v100
	v_max3_f32 v0, v0, v85, v86
	v_max3_f32 v219, v219, v101, v102
	v_max3_f32 v0, v0, v87, v88
	v_max3_f32 v219, v219, v103, v104
	v_max3_f32 v0, v0, v89, v90
	v_max3_f32 v219, v219, v105, v106
	v_max3_f32 v0, v0, v91, v92
	v_max3_f32 v219, v219, v107, v108
	v_max3_f32 v0, v0, v93, v94
	v_max3_f32 v219, v219, v109, v110
	v_max3_f32 v0, v0, v95, v111
	v_max_f32_e32 v0, v0, v219
	v_mov_b32_e32 v219, v0
	s_nop 1
	v_permlane32_swap_b32_e32 v0, v219
	v_max3_f32 v219, v217, v0, v219
	v_cmp_gt_f32_e32 vcc, v219, v217
	s_cbranch_vccz .LBB0_851
	v_sub_f32_e32 v0, v217, v219
	v_exp_f32_e32 v0, v0
	s_nop 0
	v_pk_mul_f32 v[78:79], v[78:79], v[0:1] op_sel_hi:[1,0]
	v_pk_mul_f32 v[76:77], v[76:77], v[0:1] op_sel_hi:[1,0]
	v_pk_mul_f32 v[74:75], v[74:75], v[0:1] op_sel_hi:[1,0]
	v_pk_mul_f32 v[72:73], v[72:73], v[0:1] op_sel_hi:[1,0]
	v_pk_mul_f32 v[70:71], v[70:71], v[0:1] op_sel_hi:[1,0]
	v_pk_mul_f32 v[68:69], v[68:69], v[0:1] op_sel_hi:[1,0]
	v_pk_mul_f32 v[66:67], v[66:67], v[0:1] op_sel_hi:[1,0]
	v_pk_mul_f32 v[64:65], v[64:65], v[0:1] op_sel_hi:[1,0]
	v_pk_mul_f32 v[62:63], v[62:63], v[0:1] op_sel_hi:[1,0]
	v_pk_mul_f32 v[60:61], v[60:61], v[0:1] op_sel_hi:[1,0]
	v_pk_mul_f32 v[58:59], v[58:59], v[0:1] op_sel_hi:[1,0]
	v_pk_mul_f32 v[56:57], v[56:57], v[0:1] op_sel_hi:[1,0]
	v_pk_mul_f32 v[54:55], v[54:55], v[0:1] op_sel_hi:[1,0]
	v_pk_mul_f32 v[52:53], v[52:53], v[0:1] op_sel_hi:[1,0]
	v_pk_mul_f32 v[50:51], v[50:51], v[0:1] op_sel_hi:[1,0]
	v_pk_mul_f32 v[48:49], v[48:49], v[0:1] op_sel_hi:[1,0]
	v_pk_mul_f32 v[46:47], v[46:47], v[0:1] op_sel_hi:[1,0]
	v_pk_mul_f32 v[44:45], v[44:45], v[0:1] op_sel_hi:[1,0]
	v_pk_mul_f32 v[42:43], v[42:43], v[0:1] op_sel_hi:[1,0]
	v_pk_mul_f32 v[40:41], v[40:41], v[0:1] op_sel_hi:[1,0]
	v_pk_mul_f32 v[38:39], v[38:39], v[0:1] op_sel_hi:[1,0]
	v_pk_mul_f32 v[36:37], v[36:37], v[0:1] op_sel_hi:[1,0]
	v_pk_mul_f32 v[34:35], v[34:35], v[0:1] op_sel_hi:[1,0]
	v_pk_mul_f32 v[32:33], v[32:33], v[0:1] op_sel_hi:[1,0]
	v_pk_mul_f32 v[30:31], v[30:31], v[0:1] op_sel_hi:[1,0]
	v_pk_mul_f32 v[28:29], v[28:29], v[0:1] op_sel_hi:[1,0]
	v_pk_mul_f32 v[26:27], v[26:27], v[0:1] op_sel_hi:[1,0]
	v_pk_mul_f32 v[24:25], v[24:25], v[0:1] op_sel_hi:[1,0]
	v_pk_mul_f32 v[22:23], v[22:23], v[0:1] op_sel_hi:[1,0]
	v_pk_mul_f32 v[20:21], v[20:21], v[0:1] op_sel_hi:[1,0]
	v_pk_mul_f32 v[18:19], v[18:19], v[0:1] op_sel_hi:[1,0]
	v_pk_mul_f32 v[16:17], v[16:17], v[0:1] op_sel_hi:[1,0]
	v_mul_f32_e32 v215, v215, v0
; #define LAS __attribute__((address_space(3)))
; DI unsigned cvtpk(float lo, float hi) { f32x2_t v = {lo, hi}; bf16x2_t b = __builtin_convertvector(v, bf16x2_t); return __builtin_bit_cast(unsigned, b); }
; template <int... I> DI void at_pv_all(u32x4 (&fr)[AT_KR], unsigned vaddr, const bf16x8 (&pf)[4], f32x16 (&o)[4], std::integer_sequence<int, I...>) { (at_pv_step<I>(fr, vaddr, pf, o), ...); }
; template <int DQK, bool QNORM, bool ONORM> DI void attn_unit(const Ctx& C, const AttnUnit& U) {
;     ...
;     auto lstore = [&](int buf) {
;         LAS unsigned char* kb = C.lds + AT_K0 + buf * AT_KSZ; LAS unsigned char* vb = C.lds + AT_V0 + buf * AT_VSZ;
; #pragma unroll
;         for (int i = 0; i < NKC; ++i) *(LAS u32x4*)(kb + krow[i] * KP + 16 * kc16[i]) = kreg[i];
;         *(LAS u32x2*)(vb + vdv0 * 136 + 16 * vk8) = (u32x2){vreg[0].x, vreg[0].y}; *(LAS u32x2*)(vb + vdv0 * 136 + 16 * vk8 + 8) = (u32x2){vreg[0].z, vreg[0].w};
;         *(LAS u32x2*)(vb + (vdv0 + 64) * 136 + 16 * vk8) = (u32x2){vreg[1].x, vreg[1].y}; *(LAS u32x2*)(vb + (vdv0 + 64) * 136 + 16 * vk8 + 8) = (u32x2){vreg[1].z, vreg[1].w};
;     };
;     ...
;             float ls = 0.f;
; #pragma unroll
;             for (int r = 0; r < 16; ++r) { s0[r] = __builtin_amdgcn_exp2f(s0[r] - mnew); s1[r] = __builtin_amdgcn_exp2f(s1[r] - mnew); ls += s0[r] + s1[r]; }
;             lrun += ls;
;             bf16x8 pf[4];
; #pragma unroll
;             for (int s = 0; s < 2; ++s) { u32x4 a, b;
;                 a.x = cvtpk(s0[8 * s], s0[8 * s + 1]); a.y = cvtpk(s0[8 * s + 2], s0[8 * s + 3]); a.z = cvtpk(s0[8 * s + 4], s0[8 * s + 5]); a.w = cvtpk(s0[8 * s + 6], s0[8 * s + 7]);
;                 b.x = cvtpk(s1[8 * s], s1[8 * s + 1]); b.y = cvtpk(s1[8 * s + 2], s1[8 * s + 3]); b.z = cvtpk(s1[8 * s + 4], s1[8 * s + 5]); b.w = cvtpk(s1[8 * s + 6], s1[8 * s + 7]);
;                 pf[s] = __builtin_bit_cast(bf16x8, a); pf[2 + s] = __builtin_bit_cast(bf16x8, b); }
;             at_pv_all(fr, vaddr, pf, o, std::make_integer_sequence<int, 16>{});
.LBB0_851:
	v_add_u32_e32 v0, 0x2200, v14
	v_add_u32_e32 v253, 0x3300, v14
	ds_read2_b64 v[248:251], v0 offset0:4 offset1:6
	v_sub_f32_e32 v80, v80, v219
	v_exp_f32_e32 v80, v80
	v_sub_f32_e32 v81, v81, v219
	v_exp_f32_e32 v81, v81
	v_sub_f32_e32 v82, v82, v219
	v_exp_f32_e32 v82, v82
	v_sub_f32_e32 v83, v83, v219
	v_exp_f32_e32 v83, v83
	v_add_f32_e32 v252, v80, v81
	v_sub_f32_e32 v84, v84, v219
	v_exp_f32_e32 v84, v84
	v_add_f32_e32 v252, v252, v82
	v_sub_f32_e32 v85, v85, v219
	v_exp_f32_e32 v85, v85
	v_add_f32_e32 v252, v252, v83
	v_sub_f32_e32 v86, v86, v219
	v_exp_f32_e32 v86, v86
	v_add_f32_e32 v252, v252, v84
	v_sub_f32_e32 v87, v87, v219
	v_exp_f32_e32 v87, v87
	v_add_f32_e32 v252, v252, v85
	v_sub_f32_e32 v88, v88, v219
	v_exp_f32_e32 v88, v88
	v_add_f32_e32 v252, v252, v86
	v_sub_f32_e32 v89, v89, v219
	v_exp_f32_e32 v89, v89
	v_add_f32_e32 v252, v252, v87
	v_sub_f32_e32 v90, v90, v219
	v_exp_f32_e32 v90, v90
	v_add_f32_e32 v252, v252, v88
	v_sub_f32_e32 v91, v91, v219
	v_exp_f32_e32 v91, v91
	v_add_f32_e32 v252, v252, v89
	v_sub_f32_e32 v92, v92, v219
	v_exp_f32_e32 v92, v92
	v_add_f32_e32 v252, v252, v90
	v_sub_f32_e32 v93, v93, v219
	v_exp_f32_e32 v93, v93
	v_add_f32_e32 v252, v252, v91
	v_sub_f32_e32 v94, v94, v219
	v_exp_f32_e32 v94, v94
	v_add_f32_e32 v252, v252, v92
	v_sub_f32_e32 v95, v95, v219
	v_exp_f32_e32 v95, v95
	v_add_f32_e32 v252, v252, v93
	v_add_f32_e32 v252, v252, v94
	v_add_f32_e32 v252, v252, v95
	v_cvt_pk_bf16_f32 v80, v80, v81
	v_cvt_pk_bf16_f32 v81, v82, v83
	v_cvt_pk_bf16_f32 v82, v84, v85
	v_cvt_pk_bf16_f32 v83, v86, v87
	v_cvt_pk_bf16_f32 v88, v88, v89
	v_cvt_pk_bf16_f32 v89, v90, v91
	v_cvt_pk_bf16_f32 v90, v92, v93
	v_cvt_pk_bf16_f32 v91, v94, v95
	ds_read2_b64 v[84:87], v15 offset0:4 offset1:6
	ds_read2_b64 v[92:95], v0 offset0:0 offset1:2
	s_waitcnt lgkmcnt(3)
	v_mfma_f32_32x32x16_bf16 v[64:79], v[184:187], v[80:83], v[64:79]
	ds_read2_b64 v[184:187], v253 offset0:0 offset1:2
	v_sub_f32_e32 v96, v96, v219
	v_exp_f32_e32 v96, v96
	v_sub_f32_e32 v97, v97, v219
	v_exp_f32_e32 v97, v97
	v_sub_f32_e32 v98, v98, v219
	v_exp_f32_e32 v98, v98
	v_add_f32_e32 v252, v252, v96
	v_sub_f32_e32 v99, v99, v219
	v_mfma_f32_32x32x16_bf16 v[64:79], v[180:183], v[88:91], v[64:79]
	ds_read2_b64 v[180:183], v253 offset0:4 offset1:6
	v_exp_f32_e32 v99, v99
	v_add_f32_e32 v252, v252, v97
	v_sub_f32_e32 v100, v100, v219
	v_exp_f32_e32 v100, v100
	v_add_f32_e32 v252, v252, v98
	v_sub_f32_e32 v101, v101, v219
	v_exp_f32_e32 v101, v101
	v_add_f32_e32 v252, v252, v99
	v_mfma_f32_32x32x16_bf16 v[48:63], v[2:5], v[80:83], v[48:63]
	ds_read2_b64 v[2:5], v15 offset0:8 offset1:10
	v_sub_f32_e32 v102, v102, v219
	v_exp_f32_e32 v102, v102
	v_add_f32_e32 v252, v252, v100
	v_sub_f32_e32 v103, v103, v219
	v_exp_f32_e32 v103, v103
	v_add_f32_e32 v252, v252, v101
	v_sub_f32_e32 v104, v104, v219
	v_exp_f32_e32 v104, v104
	s_waitcnt lgkmcnt(4)
	v_mfma_f32_32x32x16_bf16 v[48:63], v[84:87], v[88:91], v[48:63]
	ds_read2_b64 v[84:87], v15 offset0:12 offset1:14
	v_add_f32_e32 v252, v252, v102
	v_sub_f32_e32 v105, v105, v219
	v_exp_f32_e32 v105, v105
	v_add_f32_e32 v252, v252, v103
	v_sub_f32_e32 v106, v106, v219
	v_exp_f32_e32 v106, v106
	v_add_f32_e32 v252, v252, v104
	v_sub_f32_e32 v107, v107, v219
	s_waitcnt lgkmcnt(4)
	v_mfma_f32_32x32x16_bf16 v[32:47], v[92:95], v[80:83], v[32:47]
	ds_read2_b64 v[92:95], v0 offset0:8 offset1:10
	v_exp_f32_e32 v107, v107
	v_add_f32_e32 v252, v252, v105
	v_sub_f32_e32 v108, v108, v219
	v_exp_f32_e32 v108, v108
	v_add_f32_e32 v252, v252, v106
	v_sub_f32_e32 v109, v109, v219
	v_exp_f32_e32 v109, v109
	v_add_f32_e32 v252, v252, v107
	s_waitcnt lgkmcnt(7)
	v_mfma_f32_32x32x16_bf16 v[32:47], v[248:251], v[88:91], v[32:47]
	ds_read2_b64 v[248:251], v0 offset0:12 offset1:14
	v_sub_f32_e32 v110, v110, v219
	v_exp_f32_e32 v110, v110
	v_add_f32_e32 v252, v252, v108
	v_sub_f32_e32 v111, v111, v219
	v_exp_f32_e32 v111, v111
	v_add_f32_e32 v252, v252, v109
	v_add_f32_e32 v252, v252, v110
	v_add_f32_e32 v252, v252, v111
	s_waitcnt lgkmcnt(5)
	v_mfma_f32_32x32x16_bf16 v[16:31], v[184:187], v[80:83], v[16:31]
	v_mov_b32_e32 v217, v219
	v_cvt_pk_bf16_f32 v96, v96, v97
	v_cvt_pk_bf16_f32 v97, v98, v99
	v_cvt_pk_bf16_f32 v98, v100, v101
	v_cvt_pk_bf16_f32 v99, v102, v103
	v_cvt_pk_bf16_f32 v104, v104, v105
	v_cvt_pk_bf16_f32 v105, v106, v107
	v_cvt_pk_bf16_f32 v106, v108, v109
	s_waitcnt lgkmcnt(4)
	v_mfma_f32_32x32x16_bf16 v[16:31], v[180:183], v[88:91], v[16:31]
	v_cvt_pk_bf16_f32 v107, v110, v111
	ds_read2_b64 v[100:103], v253 offset0:8 offset1:10
	ds_read2_b64 v[108:111], v253 offset0:12 offset1:14
	v_add_f32_e32 v215, v215, v252
	s_andn2_b64 vcc, exec, s[16:17]
	s_cbranch_vccnz .Lat_pvb_nols
	v_mfma_f32_32x32x16_bf16 v[64:79], v[10:13], v[96:99], v[64:79]
	s_and_b32 s46, s44, 1
	s_mul_i32 s47, s46, 0x6400
	v_add3_u32 v0, s47, v224, v225
	v_mfma_f32_32x32x16_bf16 v[64:79], v[6:9], v[104:107], v[64:79]
	s_waitcnt vmcnt(4)
	ds_write_b128 v0, v[136:139]
	v_add3_u32 v0, s47, v226, v227
	s_waitcnt lgkmcnt(6)
	v_mfma_f32_32x32x16_bf16 v[48:63], v[2:5], v[96:99], v[48:63]
	s_waitcnt vmcnt(3)
	ds_write_b128 v0, v[140:143]
	v_add3_u32 v0, s47, v228, v229
	s_waitcnt lgkmcnt(6)
	v_mfma_f32_32x32x16_bf16 v[48:63], v[84:87], v[104:107], v[48:63]
	s_mulk_i32 s46, 0x4400
	s_waitcnt vmcnt(2)
	ds_write_b128 v0, v[144:147]
	s_waitcnt lgkmcnt(6)
	v_mfma_f32_32x32x16_bf16 v[32:47], v[92:95], v[96:99], v[32:47]
	v_add_u32_e32 v0, s46, v230
	v_add_u32_e32 v219, 0xc800, v0
	v_add_u32_e32 v0, 0xea00, v0
	s_waitcnt lgkmcnt(5)
	v_mfma_f32_32x32x16_bf16 v[32:47], v[248:251], v[104:107], v[32:47]
	s_waitcnt vmcnt(1)
	ds_write2_b64 v219, v[172:173], v[174:175] offset1:1
	s_waitcnt vmcnt(0)
	s_waitcnt lgkmcnt(5)
	v_mfma_f32_32x32x16_bf16 v[16:31], v[100:103], v[96:99], v[16:31]
	ds_write2_b64 v0, v[176:177], v[178:179] offset1:1
	s_waitcnt lgkmcnt(5)
	v_mfma_f32_32x32x16_bf16 v[16:31], v[108:111], v[104:107], v[16:31]
	s_branch .LBB0_854
.Lat_pvb_nols:
	v_mfma_f32_32x32x16_bf16 v[64:79], v[10:13], v[96:99], v[64:79]
	v_mfma_f32_32x32x16_bf16 v[64:79], v[6:9], v[104:107], v[64:79]
	s_waitcnt lgkmcnt(5)
	v_mfma_f32_32x32x16_bf16 v[48:63], v[2:5], v[96:99], v[48:63]
	s_waitcnt lgkmcnt(4)
	v_mfma_f32_32x32x16_bf16 v[48:63], v[84:87], v[104:107], v[48:63]
	s_waitcnt lgkmcnt(3)
	v_mfma_f32_32x32x16_bf16 v[32:47], v[92:95], v[96:99], v[32:47]
	s_waitcnt lgkmcnt(2)
	v_mfma_f32_32x32x16_bf16 v[32:47], v[248:251], v[104:107], v[32:47]
	s_waitcnt lgkmcnt(1)
	v_mfma_f32_32x32x16_bf16 v[16:31], v[100:103], v[96:99], v[16:31]
	s_waitcnt lgkmcnt(0)
	v_mfma_f32_32x32x16_bf16 v[16:31], v[108:111], v[104:107], v[16:31]
	s_branch .LBB0_854
